# second P1 sample in_proj tile instance (even workgroups, after the GEMM units) also staged through LDS-DMA; on top of v63
# speedup vs baseline: 1.0104x; 1.0048x over previous
.LBB0_666:
	s_mul_hi_i32 s12, s57, 0x2aaaaaab
	s_lshr_b32 s13, s12, 31
	s_ashr_i32 s12, s12, 3
	s_add_i32 s27, s12, s13
	s_mul_i32 s12, s27, 0xffffffd0
	s_add_i32 s60, s57, s12
	s_mul_i32 s12, s27, 0xfffff400
	s_add_i32 s26, s34, s12
	s_and_b32 s12, s26, 0xffffff00
	s_and_b32 s13, s36, 0x60
	s_or_b32 s12, s12, s13
	s_ashr_i32 s13, s12, 31
	s_lshl_b64 s[28:29], s[12:13], 11
	s_add_u32 s28, s3, s28
	s_addc_u32 s29, s39, s29
	s_bitset1_b32 s12, 7
	s_ashr_i32 s13, s12, 31
	v_mov_b32_e32 v37, v228
	s_lshl_b64 s[12:13], s[12:13], 11
	s_add_u32 s30, s3, s12
	v_and_b32_e32 v122, 31, v37
	v_ashrrev_i32_e32 v123, 5, v37
	s_addc_u32 s31, s39, s13
	s_lshl_b32 s12, s27, 5
	s_ashr_i32 s13, s12, 31
	s_lshl_b64 s[64:65], s[12:13], 11
	s_add_u32 s64, s58, s64
	s_addc_u32 s65, s59, s65
	s_mov_b32 s101, m0
	s_mul_i32 s100, s2, 0x180
	v_lshrrev_b32_e32 v14, 2, v37
	v_bfe_u32 v15, v37, 4, 2
	v_lshlrev_b32_e32 v14, 11, v14
	v_xor_b32_e32 v15, v15, v37
	v_bfe_u32 v16, v122, 2, 2
	v_and_b32_e32 v15, 3, v15
	v_xor_b32_e32 v16, v16, v123
	v_lshl_or_b32 v14, v15, 4, v14
	v_lshlrev_b32_e32 v16, 4, v16
	v_lshl_or_b32 v15, v122, 6, v16
	v_add_u32_e32 v15, s100, v15
	v_xor_b32_e32 v16, 32, v15
	s_add_u32 s98, s28, s0
	s_addc_u32 s99, s29, 0
	s_add_i32 m0, s100, 0x0
	s_nop 0
	global_load_lds_dwordx4 v14, s[98:99]
	s_add_u32 s98, s28, s0
	s_addc_u32 s99, s29, 0
	s_add_u32 s98, s98, 0x8000
	s_addc_u32 s99, s99, 0
	s_add_i32 m0, s100, 0x400
	s_nop 0
	global_load_lds_dwordx4 v14, s[98:99]
	s_add_u32 s98, s30, s0
	s_addc_u32 s99, s31, 0
	s_add_i32 m0, s100, 0x800
	s_nop 0
	global_load_lds_dwordx4 v14, s[98:99]
	s_add_u32 s98, s30, s0
	s_addc_u32 s99, s31, 0
	s_add_u32 s98, s98, 0x8000
	s_addc_u32 s99, s99, 0
	s_add_i32 m0, s100, 0xc00
	s_nop 0
	global_load_lds_dwordx4 v14, s[98:99]
	s_add_u32 s98, s64, s0
	s_addc_u32 s99, s65, 0
	s_add_u32 s98, s98, 0x2000000
	s_addc_u32 s99, s99, 0
	s_add_i32 m0, s100, 0x1000
	s_nop 0
	global_load_lds_dwordx4 v14, s[98:99]
	s_add_u32 s98, s64, s0
	s_addc_u32 s99, s65, 0
	s_add_u32 s98, s98, 0x2008000
	s_addc_u32 s99, s99, 0
	s_add_i32 m0, s100, 0x1400
	s_nop 0
	global_load_lds_dwordx4 v14, s[98:99]
	s_add_u32 s98, s28, s0
	s_addc_u32 s99, s29, 0
	s_add_u32 s98, s98, 0x40
	s_addc_u32 s99, s99, 0
	s_add_i32 m0, s100, 0x1800
	s_nop 0
	global_load_lds_dwordx4 v14, s[98:99]
	s_add_u32 s98, s28, s0
	s_addc_u32 s99, s29, 0
	s_add_u32 s98, s98, 0x8040
	s_addc_u32 s99, s99, 0
	s_add_i32 m0, s100, 0x1c00
	s_nop 0
	global_load_lds_dwordx4 v14, s[98:99]
	s_add_u32 s98, s30, s0
	s_addc_u32 s99, s31, 0
	s_add_u32 s98, s98, 0x40
	s_addc_u32 s99, s99, 0
	s_add_i32 m0, s100, 0x2000
	s_nop 0
	global_load_lds_dwordx4 v14, s[98:99]
	s_add_u32 s98, s30, s0
	s_addc_u32 s99, s31, 0
	s_add_u32 s98, s98, 0x8040
	s_addc_u32 s99, s99, 0
	s_add_i32 m0, s100, 0x2400
	s_nop 0
	global_load_lds_dwordx4 v14, s[98:99]
	s_add_u32 s98, s64, s0
	s_addc_u32 s99, s65, 0
	s_add_u32 s98, s98, 0x2000040
	s_addc_u32 s99, s99, 0
	s_add_i32 m0, s100, 0x2800
	s_nop 0
	global_load_lds_dwordx4 v14, s[98:99]
	s_add_u32 s98, s64, s0
	s_addc_u32 s99, s65, 0
	s_add_u32 s98, s98, 0x2008040
	s_addc_u32 s99, s99, 0
	s_add_i32 m0, s100, 0x2c00
	s_nop 0
	global_load_lds_dwordx4 v14, s[98:99]
	s_waitcnt vmcnt(6)
	ds_read_b128 v[2:5], v15
	ds_read_b128 v[6:9], v15 offset:2048
	ds_read_b128 v[10:13], v15 offset:4096
	ds_read_b128 v[38:41], v16
	ds_read_b128 v[42:45], v16 offset:2048
	ds_read_b128 v[46:49], v16 offset:4096
	s_waitcnt lgkmcnt(0)
	s_add_u32 s98, s28, s0
	s_addc_u32 s99, s29, 0
	s_add_u32 s98, s98, 0x80
	s_addc_u32 s99, s99, 0
	s_add_i32 m0, s100, 0x0
	s_nop 0
	global_load_lds_dwordx4 v14, s[98:99]
	s_add_u32 s98, s28, s0
	s_addc_u32 s99, s29, 0
	s_add_u32 s98, s98, 0x8080
	s_addc_u32 s99, s99, 0
	s_add_i32 m0, s100, 0x400
	s_nop 0
	global_load_lds_dwordx4 v14, s[98:99]
	s_add_u32 s98, s30, s0
	s_addc_u32 s99, s31, 0
	s_add_u32 s98, s98, 0x80
	s_addc_u32 s99, s99, 0
	s_add_i32 m0, s100, 0x800
	s_nop 0
	global_load_lds_dwordx4 v14, s[98:99]
	s_add_u32 s98, s30, s0
	s_addc_u32 s99, s31, 0
	s_add_u32 s98, s98, 0x8080
	s_addc_u32 s99, s99, 0
	s_add_i32 m0, s100, 0xc00
	s_nop 0
	global_load_lds_dwordx4 v14, s[98:99]
	s_add_u32 s98, s64, s0
	s_addc_u32 s99, s65, 0
	s_add_u32 s98, s98, 0x2000080
	s_addc_u32 s99, s99, 0
	s_add_i32 m0, s100, 0x1000
	s_nop 0
	global_load_lds_dwordx4 v14, s[98:99]
	s_add_u32 s98, s64, s0
	s_addc_u32 s99, s65, 0
	s_add_u32 s98, s98, 0x2008080
	s_addc_u32 s99, s99, 0
	s_add_i32 m0, s100, 0x1400
	s_nop 0
	global_load_lds_dwordx4 v14, s[98:99]
	s_waitcnt vmcnt(6)
	ds_read_b128 v[54:57], v15 offset:6144
	ds_read_b128 v[62:65], v15 offset:8192
	ds_read_b128 v[50:53], v15 offset:10240
	ds_read_b128 v[58:61], v16 offset:6144
	ds_read_b128 v[66:69], v16 offset:8192
	ds_read_b128 v[70:73], v16 offset:10240
	s_waitcnt lgkmcnt(0)
	s_add_u32 s98, s28, s0
	s_addc_u32 s99, s29, 0
	s_add_u32 s98, s98, 0xc0
	s_addc_u32 s99, s99, 0
	s_add_i32 m0, s100, 0x1800
	s_nop 0
	global_load_lds_dwordx4 v14, s[98:99]
	s_add_u32 s98, s28, s0
	s_addc_u32 s99, s29, 0
	s_add_u32 s98, s98, 0x80c0
	s_addc_u32 s99, s99, 0
	s_add_i32 m0, s100, 0x1c00
	s_nop 0
	global_load_lds_dwordx4 v14, s[98:99]
	s_add_u32 s98, s30, s0
	s_addc_u32 s99, s31, 0
	s_add_u32 s98, s98, 0xc0
	s_addc_u32 s99, s99, 0
	s_add_i32 m0, s100, 0x2000
	s_nop 0
	global_load_lds_dwordx4 v14, s[98:99]
	s_add_u32 s98, s30, s0
	s_addc_u32 s99, s31, 0
	s_add_u32 s98, s98, 0x80c0
	s_addc_u32 s99, s99, 0
	s_add_i32 m0, s100, 0x2400
	s_nop 0
	global_load_lds_dwordx4 v14, s[98:99]
	s_add_u32 s98, s64, s0
	s_addc_u32 s99, s65, 0
	s_add_u32 s98, s98, 0x20000c0
	s_addc_u32 s99, s99, 0
	s_add_i32 m0, s100, 0x2800
	s_nop 0
	global_load_lds_dwordx4 v14, s[98:99]
	s_add_u32 s98, s64, s0
	s_addc_u32 s99, s65, 0
	s_add_u32 s98, s98, 0x20080c0
	s_addc_u32 s99, s99, 0
	s_add_i32 m0, s100, 0x2c00
	s_nop 0
	global_load_lds_dwordx4 v14, s[98:99]
	s_waitcnt vmcnt(6)
	ds_read_b128 v[78:81], v15
	ds_read_b128 v[86:89], v15 offset:2048
	ds_read_b128 v[74:77], v15 offset:4096
	ds_read_b128 v[82:85], v16
	ds_read_b128 v[90:93], v16 offset:2048
	ds_read_b128 v[94:97], v16 offset:4096
	s_waitcnt vmcnt(0)
	ds_read_b128 v[102:105], v15 offset:6144
	ds_read_b128 v[110:113], v15 offset:8192
	ds_read_b128 v[98:101], v15 offset:10240
	ds_read_b128 v[106:109], v16 offset:6144
	ds_read_b128 v[114:117], v16 offset:8192
	ds_read_b128 v[118:121], v16 offset:10240
	s_mov_b32 m0, s101
	s_waitcnt lgkmcnt(0)
	v_mfma_f32_32x32x16_bf16 v[18:33], v[2:5], v[10:13], 0
	v_or_b32_e32 v34, s2, v122
	v_mul_lo_u32 v34, v34, s55
	s_ashr_i32 s61, s60, 3
	v_mfma_f32_32x32x16_bf16 v[2:17], v[6:9], v[10:13], 0
	v_mfma_f32_32x32x16_bf16 v[18:33], v[38:41], v[46:49], v[18:33]
	v_lshlrev_b32_e32 v38, 4, v123
	v_add3_u32 v34, 0, v34, v38
	v_mfma_f32_32x32x16_bf16 v[2:17], v[42:45], v[46:49], v[2:17]
	v_mfma_f32_32x32x16_bf16 v[18:33], v[54:57], v[50:53], v[18:33]
	v_mfma_f32_32x32x16_bf16 v[2:17], v[62:65], v[50:53], v[2:17]
	v_mfma_f32_32x32x16_bf16 v[18:33], v[58:61], v[70:73], v[18:33]
	v_mfma_f32_32x32x16_bf16 v[2:17], v[66:69], v[70:73], v[2:17]
	v_mfma_f32_32x32x16_bf16 v[18:33], v[78:81], v[74:77], v[18:33]
	v_mfma_f32_32x32x16_bf16 v[2:17], v[86:89], v[74:77], v[2:17]
	v_mfma_f32_32x32x16_bf16 v[18:33], v[82:85], v[94:97], v[18:33]
	v_mfma_f32_32x32x16_bf16 v[2:17], v[90:93], v[94:97], v[2:17]
	v_mfma_f32_32x32x16_bf16 v[18:33], v[102:105], v[98:101], v[18:33]
	v_mfma_f32_32x32x16_bf16 v[2:17], v[110:113], v[98:101], v[2:17]
	v_mfma_f32_32x32x16_bf16 v[18:33], v[106:109], v[118:121], v[18:33]
	v_mfma_f32_32x32x16_bf16 v[2:17], v[114:117], v[118:121], v[2:17]
	s_nop 10
	s_barrier
	ds_write_b128 v34, v[18:21]
	ds_write_b128 v34, v[2:5] offset:128
	ds_write_b128 v34, v[22:25] offset:32
	ds_write_b128 v34, v[6:9] offset:160
	ds_write_b128 v34, v[26:29] offset:64
	ds_write_b128 v34, v[10:13] offset:192
	ds_write_b128 v34, v[30:33] offset:96
	ds_write_b128 v34, v[14:17] offset:224
	v_add_u32_e32 v2, s33, v37
	v_ashrrev_i32_e32 v13, 4, v2
	v_lshlrev_b32_e32 v2, 2, v37
	v_and_b32_e32 v20, 60, v2
	v_lshlrev_b32_e32 v12, 2, v20
	v_mul_lo_u32 v2, v13, s55
	v_add3_u32 v21, 0, v12, v2
	s_waitcnt lgkmcnt(0)
	s_barrier
	ds_read_b128 v[2:5], v21
	ds_read_b128 v[6:9], v21 offset:8704
	ds_read_b128 v[14:17], v21 offset:17408
	s_waitcnt lgkmcnt(2)
	v_pk_add_f32 v[4:5], v[4:5], 0 op_sel_hi:[1,0]
	v_pk_add_f32 v[10:11], v[2:3], 0 op_sel_hi:[1,0]
	s_waitcnt lgkmcnt(1)
	v_pk_add_f32 v[8:9], v[4:5], v[8:9]
	ds_read_b128 v[2:5], v21 offset:26112
	v_pk_add_f32 v[10:11], v[10:11], v[6:7]
	s_waitcnt lgkmcnt(1)
	v_pk_add_f32 v[16:17], v[8:9], v[16:17]
	ds_read_b128 v[6:9], v21 offset:34816
	v_pk_add_f32 v[10:11], v[10:11], v[14:15]
	s_waitcnt lgkmcnt(1)
	v_pk_add_f32 v[14:15], v[16:17], v[4:5]
	v_pk_add_f32 v[16:17], v[10:11], v[2:3]
	ds_read_b128 v[2:5], v21 offset:43520
	s_waitcnt lgkmcnt(1)
	v_pk_add_f32 v[18:19], v[14:15], v[8:9]
	ds_read_b128 v[8:11], v21 offset:52224
	v_pk_add_f32 v[6:7], v[16:17], v[6:7]
	ds_read_b128 v[14:17], v21 offset:60928
	s_waitcnt lgkmcnt(2)
	v_pk_add_f32 v[2:3], v[6:7], v[2:3]
	v_add_u32_e32 v6, s12, v13
	v_pk_add_f32 v[4:5], v[18:19], v[4:5]
	v_ashrrev_i32_e32 v7, 31, v6
	s_waitcnt lgkmcnt(1)
	v_pk_add_f32 v[4:5], v[4:5], v[10:11]
	v_pk_add_f32 v[2:3], v[2:3], v[8:9]
	v_lshlrev_b64 v[10:11], 9, v[6:7]
	s_and_b32 s12, s26, 0x1c0
	s_waitcnt lgkmcnt(0)
	v_pk_add_f32 v[4:5], v[4:5], v[16:17]
	v_pk_add_f32 v[2:3], v[2:3], v[14:15]
	v_or3_b32 v10, v10, s12, v20
	s_cmp_gt_i32 s61, 1
	s_mov_b64 s[12:13], -1
	s_barrier
	s_cbranch_scc0 .LBB0_679
	s_mov_b64 s[30:31], -1
	s_mov_b64 s[12:13], 0
	s_cmp_lt_i32 s61, 4
	s_mov_b64 s[26:27], 0
	s_mov_b64 s[28:29], 0
	s_cbranch_scc1 .LBB0_672
	s_cmp_lg_u32 s61, 4
	s_mov_b64 s[26:27], -1
	s_cselect_b64 s[28:29], -1, 0
	s_cbranch_execz .LBB0_673
